# hgrn combine items: 8-lane sum via DPP instead of 3 ds_bpermute round trips (on top of qk-prep DPP)
# speedup vs baseline: 1.0015x; 1.0015x over previous
.LBB0_223:
	v_mov_b32_e32 v0, v1
	s_add_i32 s21, s21, s81
	v_mbcnt_lo_u32_b32 v0, -1, v0
	v_mbcnt_hi_u32_b32 v0, -1, v0
	v_add_u32_e32 v0, s80, v0
	s_nop 0
	v_ashrrev_i32_e32 v6, 3, v0
	s_waitcnt lgkmcnt(0)
	v_add_u32_e32 v2, s20, v6
	v_ashrrev_i32_e32 v2, 2, v2
	v_ashrrev_i32_e32 v3, 31, v2
	v_lshlrev_b64 v[4:5], 9, v[2:3]
	v_lshlrev_b32_e32 v3, 7, v6
	v_and_b32_e32 v8, 0x180, v3
	v_lshlrev_b32_e32 v0, 4, v0
	v_mov_b64_e32 v[6:7], s[58:59]
	v_and_b32_e32 v22, 0x70, v0
	v_mad_i64_i32 v[2:3], s[24:25], v2, s31, v[6:7]
	v_lshlrev_b32_e32 v0, 1, v8
	v_lshl_add_u64 v[2:3], v[2:3], 0, v[0:1]
	v_lshlrev_b32_e32 v0, 1, v22
	v_or3_b32 v4, v4, v8, v22
	v_lshl_add_u64 v[2:3], v[2:3], 0, v[0:1]
	v_lshlrev_b64 v[6:7], 1, v[4:5]
	v_lshl_add_u64 v[20:21], v[2:3], 0, s[34:35]
	v_add_co_u32_e32 v2, vcc, s2, v2
	v_lshl_add_u64 v[32:33], v[4:5], 2, s[4:5]
	v_lshl_add_u64 v[4:5], s[22:23], 0, v[6:7]
	v_addc_co_u32_e32 v3, vcc, 0, v3, vcc
	global_load_dwordx4 v[8:11], v[4:5], off
	global_load_dwordx4 v[12:15], v[4:5], off offset:16
	v_cmp_lt_i32_e32 vcc, v227, v221
	global_load_dwordx4 v[16:19], v[2:3], off
	s_nop 0
	global_load_dwordx4 v[2:5], v[20:21], off offset:16
	v_cndmask_b32_e32 v20, v220, v227, vcc
	v_cmp_lt_i32_e32 vcc, v226, v221
	v_lshlrev_b32_e32 v70, 2, v20
	v_lshlrev_b32_e32 v0, 2, v22
	v_cndmask_b32_e32 v20, v220, v226, vcc
	v_cmp_lt_i32_e32 vcc, v235, v221
	v_lshlrev_b32_e32 v71, 2, v20
	v_lshl_add_u64 v[6:7], s[28:29], 0, v[6:7]
	v_cndmask_b32_e32 v20, v220, v235, vcc
	v_lshlrev_b32_e32 v72, 2, v20
	global_load_dwordx4 v[20:23], v[32:33], off offset:48
	global_load_dwordx4 v[24:27], v[32:33], off offset:32
	global_load_dwordx4 v[28:31], v[32:33], off offset:16
	s_nop 0
	global_load_dwordx4 v[32:35], v[32:33], off
	s_add_i32 s20, s20, s30
	s_cmpk_gt_i32 s21, 0x3ff
	s_waitcnt vmcnt(0)
	v_lshlrev_b32_e32 v36, 16, v15
	v_and_b32_e32 v37, 0xffff0000, v15
	s_waitcnt vmcnt(4)
	v_and_b32_e32 v55, 0xffff0000, v4
	v_lshlrev_b32_e32 v58, 16, v3
	v_and_b32_e32 v59, 0xffff0000, v3
	v_lshlrev_b32_e32 v54, 16, v4
	v_mul_f32_e32 v4, 0xbfb8aa3b, v54
	v_exp_f32_e32 v4, v4
	v_lshlrev_b32_e32 v62, 16, v19
	v_and_b32_e32 v63, 0xffff0000, v19
	s_waitcnt vmcnt(3)
	v_pk_add_f32 v[48:49], v[22:23], v[36:37]
	v_lshlrev_b32_e32 v22, 16, v14
	v_and_b32_e32 v23, 0xffff0000, v14
	v_pk_add_f32 v[14:15], v[20:21], v[22:23]
	global_load_dwordx4 v[20:23], v0, s[26:27] offset:48
	global_load_dwordx4 v[36:39], v0, s[26:27] offset:32
	global_load_dwordx4 v[40:43], v0, s[26:27] offset:16
	global_load_dwordx4 v[44:47], v0, s[26:27]
	v_mul_f32_e32 v0, 0xbfb8aa3b, v55
	v_exp_f32_e32 v0, v0
	v_add_f32_e32 v4, 1.0, v4
	v_rcp_f32_e32 v56, v4
	v_lshlrev_b32_e32 v66, 16, v17
	v_add_f32_e32 v0, 1.0, v0
	v_rcp_f32_e32 v57, v0
	v_mul_f32_e32 v0, 0xbfb8aa3b, v58
	v_exp_f32_e32 v0, v0
	v_and_b32_e32 v67, 0xffff0000, v17
	v_pk_mul_f32 v[54:55], v[56:57], v[54:55]
	v_lshlrev_b32_e32 v56, 16, v13
	v_add_f32_e32 v0, 1.0, v0
	v_rcp_f32_e32 v60, v0
	v_mul_f32_e32 v0, 0xbfb8aa3b, v59
	v_exp_f32_e32 v0, v0
	v_and_b32_e32 v57, 0xffff0000, v13
	s_waitcnt vmcnt(6)
	v_pk_add_f32 v[26:27], v[26:27], v[56:57]
	v_pk_mul_f32 v[52:53], v[14:15], v[14:15]
	v_add_f32_e32 v0, 1.0, v0
	v_rcp_f32_e32 v61, v0
	v_pk_mul_f32 v[56:57], v[26:27], v[26:27]
	v_pk_mul_f32 v[50:51], v[48:49], v[48:49]
	v_pk_mul_f32 v[58:59], v[60:61], v[58:59]
	v_lshlrev_b32_e32 v60, 16, v12
	v_and_b32_e32 v61, 0xffff0000, v12
	v_pk_add_f32 v[12:13], v[24:25], v[60:61]
	v_lshlrev_b32_e32 v60, 16, v2
	v_mul_f32_e32 v0, 0xbfb8aa3b, v60
	v_exp_f32_e32 v0, v0
	v_and_b32_e32 v61, 0xffff0000, v2
	v_pk_mul_f32 v[24:25], v[12:13], v[12:13]
	v_add_f32_e32 v0, 1.0, v0
	v_rcp_f32_e32 v2, v0
	v_mul_f32_e32 v0, 0xbfb8aa3b, v61
	v_exp_f32_e32 v0, v0
	s_nop 0
	v_add_f32_e32 v0, 1.0, v0
	v_rcp_f32_e32 v3, v0
	v_mul_f32_e32 v0, 0xbfb8aa3b, v62
	v_exp_f32_e32 v0, v0
	v_pk_mul_f32 v[2:3], v[2:3], v[60:61]
	v_lshlrev_b32_e32 v60, 16, v11
	v_add_f32_e32 v0, 1.0, v0
	v_rcp_f32_e32 v64, v0
	v_mul_f32_e32 v0, 0xbfb8aa3b, v63
	v_exp_f32_e32 v0, v0
	v_and_b32_e32 v61, 0xffff0000, v11
	s_waitcnt vmcnt(5)
	v_pk_add_f32 v[30:31], v[30:31], v[60:61]
	v_add_f32_e32 v0, 1.0, v0
	v_rcp_f32_e32 v65, v0
	v_pk_mul_f32 v[60:61], v[30:31], v[30:31]
	v_pk_mul_f32 v[62:63], v[64:65], v[62:63]
	v_lshlrev_b32_e32 v64, 16, v10
	v_and_b32_e32 v65, 0xffff0000, v10
	v_pk_add_f32 v[10:11], v[28:29], v[64:65]
	v_lshlrev_b32_e32 v64, 16, v18
	v_mul_f32_e32 v0, 0xbfb8aa3b, v64
	v_exp_f32_e32 v0, v0
	v_and_b32_e32 v65, 0xffff0000, v18
	v_pk_mul_f32 v[28:29], v[10:11], v[10:11]
	v_add_f32_e32 v0, 1.0, v0
	v_rcp_f32_e32 v18, v0
	v_mul_f32_e32 v0, 0xbfb8aa3b, v65
	v_exp_f32_e32 v0, v0
	s_nop 0
	v_add_f32_e32 v0, 1.0, v0
	v_rcp_f32_e32 v19, v0
	v_mul_f32_e32 v0, 0xbfb8aa3b, v66
	v_exp_f32_e32 v0, v0
	v_pk_mul_f32 v[18:19], v[18:19], v[64:65]
	v_lshlrev_b32_e32 v64, 16, v9
	v_add_f32_e32 v0, 1.0, v0
	v_rcp_f32_e32 v68, v0
	v_mul_f32_e32 v0, 0xbfb8aa3b, v67
	v_exp_f32_e32 v0, v0
	v_and_b32_e32 v65, 0xffff0000, v9
	s_waitcnt vmcnt(4)
	v_pk_add_f32 v[34:35], v[34:35], v[64:65]
	v_add_f32_e32 v0, 1.0, v0
	v_rcp_f32_e32 v69, v0
	v_pk_mul_f32 v[64:65], v[34:35], v[34:35]
	v_pk_mul_f32 v[66:67], v[68:69], v[66:67]
	v_lshlrev_b32_e32 v68, 16, v8
	v_and_b32_e32 v69, 0xffff0000, v8
	v_pk_add_f32 v[8:9], v[32:33], v[68:69]
	v_lshlrev_b32_e32 v68, 16, v16
	v_mul_f32_e32 v0, 0xbfb8aa3b, v68
	v_exp_f32_e32 v0, v0
	v_and_b32_e32 v69, 0xffff0000, v16
	v_pk_mul_f32 v[32:33], v[8:9], v[8:9]
	v_add_f32_e32 v0, 1.0, v0
	v_rcp_f32_e32 v16, v0
	v_mul_f32_e32 v0, 0xbfb8aa3b, v69
	v_exp_f32_e32 v0, v0
	s_nop 0
	v_add_f32_e32 v0, 1.0, v0
	v_rcp_f32_e32 v17, v0
	v_add_f32_e32 v0, v32, v33
	v_add_f32_e32 v0, v64, v0
	v_add_f32_e32 v0, v65, v0
	v_add_f32_e32 v0, v28, v0
	v_add_f32_e32 v0, v29, v0
	v_add_f32_e32 v0, v60, v0
	v_add_f32_e32 v0, v61, v0
	v_add_f32_e32 v0, v24, v0
	v_add_f32_e32 v0, v25, v0
	v_add_f32_e32 v0, v56, v0
	v_add_f32_e32 v0, v57, v0
	v_add_f32_e32 v0, v52, v0
	v_add_f32_e32 v0, v53, v0
	v_add_f32_e32 v0, v50, v0
	v_add_f32_e32 v0, v51, v0
	v_pk_mul_f32 v[16:17], v[16:17], v[68:69]
	s_nop 1
	v_add_f32_dpp v0, v0, v0 quad_perm:[1,0,3,2] row_mask:0xf bank_mask:0xf
	s_nop 1
	v_add_f32_dpp v0, v0, v0 quad_perm:[2,3,0,1] row_mask:0xf bank_mask:0xf
	s_nop 1
	v_add_f32_dpp v0, v0, v0 row_half_mirror row_mask:0xf bank_mask:0xf
	v_fmamk_f32 v0, v0, 0x3c000000, v187
	v_cmp_gt_f32_e32 vcc, s82, v0
	v_mul_f32_e32 v4, 0x4b800000, v0
	s_nop 0
	v_cndmask_b32_e32 v0, v0, v4, vcc
	v_rsq_f32_e32 v0, v0
	s_nop 0
	v_mul_f32_e32 v4, 0x45800000, v0
	v_cndmask_b32_e32 v0, v0, v4, vcc
	v_pk_mul_f32 v[12:13], v[12:13], v[0:1] op_sel_hi:[1,0]
	v_pk_mul_f32 v[8:9], v[8:9], v[0:1] op_sel_hi:[1,0]
	s_waitcnt vmcnt(2)
	v_pk_mul_f32 v[12:13], v[36:37], v[12:13]
	s_waitcnt vmcnt(0)
	v_pk_mul_f32 v[8:9], v[44:45], v[8:9]
	v_pk_mul_f32 v[12:13], v[2:3], v[12:13]
	v_pk_mul_f32 v[2:3], v[34:35], v[0:1] op_sel_hi:[1,0]
	v_pk_mul_f32 v[8:9], v[16:17], v[8:9]
	v_pk_mul_f32 v[2:3], v[46:47], v[2:3]
	s_nop 0
	v_pk_mul_f32 v[16:17], v[66:67], v[2:3]
	v_pk_mul_f32 v[2:3], v[26:27], v[0:1] op_sel_hi:[1,0]
	s_nop 0
	v_pk_mul_f32 v[2:3], v[38:39], v[2:3]
	s_nop 0
	v_pk_mul_f32 v[24:25], v[58:59], v[2:3]
	v_pk_mul_f32 v[2:3], v[10:11], v[0:1] op_sel_hi:[1,0]
	s_nop 0
	v_pk_mul_f32 v[2:3], v[40:41], v[2:3]
	s_nop 0
	v_pk_mul_f32 v[10:11], v[18:19], v[2:3]
	v_pk_mul_f32 v[2:3], v[14:15], v[0:1] op_sel_hi:[1,0]
	s_nop 0
	v_pk_mul_f32 v[2:3], v[20:21], v[2:3]
	v_pk_mul_f32 v[20:21], v[48:49], v[0:1] op_sel_hi:[1,0]
	v_pk_mul_f32 v[14:15], v[54:55], v[2:3]
	v_pk_mul_f32 v[2:3], v[30:31], v[0:1] op_sel_hi:[1,0]
	v_pk_mul_f32 v[20:21], v[22:23], v[20:21]
	v_pk_mul_f32 v[2:3], v[42:43], v[2:3]
	s_nop 0
	v_pk_mul_f32 v[18:19], v[62:63], v[2:3]
	v_lshlrev_b32_e32 v2, 16, v5
	v_and_b32_e32 v3, 0xffff0000, v5
	v_mul_f32_e32 v4, 0xbfb8aa3b, v2
	v_mul_f32_e32 v0, 0xbfb8aa3b, v3
	v_exp_f32_e32 v4, v4
	v_exp_f32_e32 v0, v0
	v_add_f32_e32 v4, 1.0, v4
	v_add_f32_e32 v0, 1.0, v0
	v_rcp_f32_e32 v4, v4
	v_rcp_f32_e32 v5, v0
	s_nop 0
	v_pk_mul_f32 v[2:3], v[4:5], v[2:3]
	s_nop 0
	v_pk_mul_f32 v[20:21], v[2:3], v[20:21]
	v_cvt_pk_bf16_f32 v2, v8, v9
	v_cvt_pk_bf16_f32 v3, v16, v17
	v_cvt_pk_bf16_f32 v4, v10, v11
	v_cvt_pk_bf16_f32 v5, v18, v19
	global_store_dwordx4 v[6:7], v[2:5], off
	s_nop 1
	v_cvt_pk_bf16_f32 v2, v12, v13
	v_cvt_pk_bf16_f32 v3, v24, v25
	v_cvt_pk_bf16_f32 v4, v14, v15
	v_cvt_pk_bf16_f32 v5, v20, v21
	global_store_dwordx4 v[6:7], v[2:5], off offset:16
	s_cbranch_scc0 .LBB0_223

.LBB0_258:
	s_and_b64 vcc, exec, s[4:5]
	s_cbranch_vccz .LBB0_260
	v_ashrrev_i32_e32 v0, 3, v236
	s_waitcnt lgkmcnt(0)
	v_lshl_add_u32 v2, s25, 5, v0
	v_ashrrev_i32_e32 v2, 2, v2
	v_ashrrev_i32_e32 v3, 31, v2
	v_lshlrev_b64 v[4:5], 9, v[2:3]
	v_lshlrev_b32_e32 v0, 7, v0
	v_lshlrev_b32_e32 v3, 4, v236
	v_readlane_b32 s36, v252, 4
	v_and_b32_e32 v0, 0x180, v0
	v_and_b32_e32 v16, 0x70, v3
	v_readlane_b32 s4, v255, 8
	v_readlane_b32 s50, v252, 18
	v_readlane_b32 s51, v252, 19
	v_or3_b32 v4, v4, v0, v16
	v_readlane_b32 s5, v255, 9
	v_mov_b64_e32 v[6:7], s[50:51]
	v_lshlrev_b32_e32 v0, 1, v0
	v_lshl_add_u64 v[18:19], v[4:5], 2, s[4:5]
	v_mad_i64_i32 v[2:3], s[4:5], v2, s2, v[6:7]
	v_readlane_b32 s4, v255, 15
	v_lshl_add_u64 v[2:3], v[2:3], 0, v[0:1]
	v_lshlrev_b64 v[42:43], 1, v[4:5]
	v_readlane_b32 s5, v255, 16
	v_lshlrev_b32_e32 v0, 1, v16
	v_lshl_add_u64 v[2:3], v[2:3], 0, v[0:1]
	v_lshl_add_u64 v[4:5], s[4:5], 0, v[42:43]
	s_mov_b64 s[4:5], 0x6c26000
	s_mov_b32 s1, 0x6c26000
	v_lshl_add_u64 v[14:15], v[2:3], 0, s[4:5]
	v_add_co_u32_e32 v2, vcc, s1, v2
	global_load_dwordx4 v[10:13], v[4:5], off
	global_load_dwordx4 v[38:41], v[4:5], off offset:16
	v_addc_co_u32_e32 v3, vcc, 0, v3, vcc
	global_load_dwordx4 v[6:9], v[2:3], off
	s_nop 0
	global_load_dwordx4 v[2:5], v[14:15], off offset:16
	v_lshlrev_b32_e32 v26, 2, v16
	global_load_dwordx4 v[14:17], v[18:19], off offset:48
	global_load_dwordx4 v[58:61], v[18:19], off offset:32
	global_load_dwordx4 v[34:37], v[18:19], off offset:16
	global_load_dwordx4 v[30:33], v[18:19], off
	v_readlane_b32 s4, v255, 17
	v_readlane_b32 s5, v255, 18
	v_cmp_lt_i32_e32 vcc, v227, v221
	v_readlane_b32 s37, v252, 5
	v_readlane_b32 s38, v252, 6
	v_cndmask_b32_e32 v0, v220, v227, vcc
	v_lshlrev_b32_e32 v65, 2, v0
	v_cmp_lt_i32_e32 vcc, v226, v221
	v_readlane_b32 s39, v252, 7
	v_readlane_b32 s40, v252, 8
	v_cndmask_b32_e32 v0, v220, v226, vcc
	v_lshlrev_b32_e32 v64, 2, v0
	v_cmp_lt_i32_e32 vcc, v235, v221
	v_readlane_b32 s41, v252, 9
	v_readlane_b32 s42, v252, 10
	v_cndmask_b32_e32 v0, v220, v235, vcc
	v_lshlrev_b32_e32 v0, 2, v0
	v_readlane_b32 s43, v252, 11
	v_readlane_b32 s44, v252, 12
	v_readlane_b32 s45, v252, 13
	v_readlane_b32 s46, v252, 14
	v_readlane_b32 s47, v252, 15
	v_readlane_b32 s48, v252, 16
	v_readlane_b32 s49, v252, 17
	s_waitcnt vmcnt(0)
	v_lshlrev_b32_e32 v18, 16, v41
	v_and_b32_e32 v19, 0xffff0000, v41
	s_waitcnt vmcnt(5)
	v_lshlrev_b32_e32 v62, 16, v9
	s_waitcnt vmcnt(4)
	v_lshlrev_b32_e32 v50, 16, v4
	v_and_b32_e32 v51, 0xffff0000, v4
	v_mul_f32_e32 v4, 0xbfb8aa3b, v50
	v_exp_f32_e32 v4, v4
	v_lshlrev_b32_e32 v54, 16, v3
	v_and_b32_e32 v55, 0xffff0000, v3
	v_mul_f32_e32 v3, 0xbfb8aa3b, v54
	v_add_f32_e32 v4, 1.0, v4
	v_rcp_f32_e32 v52, v4
	v_mul_f32_e32 v4, 0xbfb8aa3b, v51
	v_exp_f32_e32 v4, v4
	v_exp_f32_e32 v3, v3
	v_and_b32_e32 v63, 0xffff0000, v9
	s_waitcnt vmcnt(3)
	v_pk_add_f32 v[44:45], v[16:17], v[18:19]
	v_add_f32_e32 v4, 1.0, v4
	v_rcp_f32_e32 v53, v4
	v_add_f32_e32 v3, 1.0, v3
	v_mul_f32_e32 v4, 0xbfb8aa3b, v62
	v_exp_f32_e32 v4, v4
	v_pk_mul_f32 v[50:51], v[52:53], v[50:51]
	v_lshlrev_b32_e32 v52, 16, v39
	v_and_b32_e32 v53, 0xffff0000, v39
	s_waitcnt vmcnt(2)
	v_pk_add_f32 v[52:53], v[60:61], v[52:53]
	v_rcp_f32_e32 v60, v3
	v_mul_f32_e32 v3, 0xbfb8aa3b, v55
	v_exp_f32_e32 v3, v3
	v_add_f32_e32 v4, 1.0, v4
	v_rcp_f32_e32 v66, v4
	v_mul_f32_e32 v4, 0xbfb8aa3b, v63
	v_add_f32_e32 v3, 1.0, v3
	v_rcp_f32_e32 v61, v3
	v_exp_f32_e32 v4, v4
	v_lshlrev_b32_e32 v16, 16, v40
	v_and_b32_e32 v17, 0xffff0000, v40
	v_pk_mul_f32 v[54:55], v[60:61], v[54:55]
	v_lshlrev_b32_e32 v60, 16, v38
	v_and_b32_e32 v61, 0xffff0000, v38
	v_pk_add_f32 v[38:39], v[58:59], v[60:61]
	v_lshlrev_b32_e32 v58, 16, v2
	v_and_b32_e32 v59, 0xffff0000, v2
	v_mul_f32_e32 v2, 0xbfb8aa3b, v58
	v_mul_f32_e32 v3, 0xbfb8aa3b, v59
	v_exp_f32_e32 v2, v2
	v_exp_f32_e32 v3, v3
	v_add_f32_e32 v4, 1.0, v4
	v_rcp_f32_e32 v67, v4
	v_add_f32_e32 v2, 1.0, v2
	v_add_f32_e32 v3, 1.0, v3
	v_rcp_f32_e32 v2, v2
	v_rcp_f32_e32 v3, v3
	v_pk_mul_f32 v[62:63], v[66:67], v[62:63]
	v_lshlrev_b32_e32 v66, 16, v12
	v_and_b32_e32 v67, 0xffff0000, v12
	v_pk_mul_f32 v[58:59], v[2:3], v[58:59]
	v_lshlrev_b32_e32 v2, 16, v13
	v_and_b32_e32 v3, 0xffff0000, v13
	s_waitcnt vmcnt(1)
	v_pk_add_f32 v[12:13], v[34:35], v[66:67]
	v_lshlrev_b32_e32 v66, 16, v8
	v_mul_f32_e32 v4, 0xbfb8aa3b, v66
	v_exp_f32_e32 v4, v4
	v_and_b32_e32 v67, 0xffff0000, v8
	v_pk_add_f32 v[40:41], v[14:15], v[16:17]
	global_load_dwordx4 v[14:17], v26, s[4:5] offset:48
	global_load_dwordx4 v[22:25], v26, s[4:5] offset:32
	global_load_dwordx4 v[18:21], v26, s[4:5] offset:16
	s_nop 0
	global_load_dwordx4 v[26:29], v26, s[4:5]
	v_add_f32_e32 v4, 1.0, v4
	v_rcp_f32_e32 v8, v4
	v_mul_f32_e32 v4, 0xbfb8aa3b, v67
	v_exp_f32_e32 v4, v4
	v_lshlrev_b32_e32 v68, 16, v7
	v_and_b32_e32 v69, 0xffff0000, v7
	v_pk_mul_f32 v[34:35], v[12:13], v[12:13]
	v_add_f32_e32 v4, 1.0, v4
	v_rcp_f32_e32 v9, v4
	v_mul_f32_e32 v4, 0xbfb8aa3b, v68
	v_exp_f32_e32 v4, v4
	v_pk_add_f32 v[2:3], v[36:37], v[2:3]
	v_pk_mul_f32 v[8:9], v[8:9], v[66:67]
	v_lshlrev_b32_e32 v66, 16, v11
	v_add_f32_e32 v4, 1.0, v4
	v_rcp_f32_e32 v70, v4
	v_mul_f32_e32 v4, 0xbfb8aa3b, v69
	v_exp_f32_e32 v4, v4
	v_and_b32_e32 v67, 0xffff0000, v11
	s_waitcnt vmcnt(4)
	v_pk_add_f32 v[32:33], v[32:33], v[66:67]
	v_pk_mul_f32 v[36:37], v[2:3], v[2:3]
	v_add_f32_e32 v4, 1.0, v4
	v_rcp_f32_e32 v71, v4
	v_pk_mul_f32 v[66:67], v[32:33], v[32:33]
	v_pk_mul_f32 v[60:61], v[38:39], v[38:39]
	v_pk_mul_f32 v[56:57], v[52:53], v[52:53]
	v_pk_mul_f32 v[68:69], v[70:71], v[68:69]
	v_lshlrev_b32_e32 v70, 16, v10
	v_and_b32_e32 v71, 0xffff0000, v10
	v_pk_add_f32 v[10:11], v[30:31], v[70:71]
	v_lshlrev_b32_e32 v70, 16, v6
	v_mul_f32_e32 v4, 0xbfb8aa3b, v70
	v_exp_f32_e32 v4, v4
	v_and_b32_e32 v71, 0xffff0000, v6
	v_pk_mul_f32 v[30:31], v[10:11], v[10:11]
	v_pk_mul_f32 v[48:49], v[40:41], v[40:41]
	v_add_f32_e32 v4, 1.0, v4
	v_rcp_f32_e32 v6, v4
	v_mul_f32_e32 v4, 0xbfb8aa3b, v71
	v_exp_f32_e32 v4, v4
	v_pk_mul_f32 v[46:47], v[44:45], v[44:45]
	v_readlane_b32 s4, v252, 22
	v_readlane_b32 s5, v252, 23
	v_add_f32_e32 v4, 1.0, v4
	v_rcp_f32_e32 v7, v4
	v_add_f32_e32 v4, v30, v31
	v_add_f32_e32 v4, v66, v4
	v_add_f32_e32 v4, v67, v4
	v_add_f32_e32 v4, v34, v4
	v_add_f32_e32 v4, v35, v4
	v_add_f32_e32 v4, v36, v4
	v_add_f32_e32 v4, v37, v4
	v_add_f32_e32 v4, v60, v4
	v_add_f32_e32 v4, v61, v4
	v_add_f32_e32 v4, v56, v4
	v_add_f32_e32 v4, v57, v4
	v_add_f32_e32 v4, v48, v4
	v_add_f32_e32 v4, v49, v4
	v_add_f32_e32 v4, v46, v4
	v_add_f32_e32 v4, v47, v4
	v_pk_mul_f32 v[6:7], v[6:7], v[70:71]
	s_nop 1
	v_add_f32_dpp v4, v4, v4 quad_perm:[1,0,3,2] row_mask:0xf bank_mask:0xf
	s_nop 1
	v_add_f32_dpp v4, v4, v4 quad_perm:[2,3,0,1] row_mask:0xf bank_mask:0xf
	s_nop 1
	v_add_f32_dpp v0, v4, v4 row_half_mirror row_mask:0xf bank_mask:0xf
	v_fmamk_f32 v0, v0, 0x3c000000, v187
	v_cmp_gt_f32_e32 vcc, s82, v0
	v_mul_f32_e32 v4, 0x4b800000, v0
	s_nop 0
	v_cndmask_b32_e32 v0, v0, v4, vcc
	v_rsq_f32_e32 v0, v0
	s_nop 0
	v_mul_f32_e32 v4, 0x45800000, v0
	v_cndmask_b32_e32 v0, v0, v4, vcc
	v_pk_mul_f32 v[12:13], v[12:13], v[0:1] op_sel_hi:[1,0]
	v_pk_mul_f32 v[10:11], v[10:11], v[0:1] op_sel_hi:[1,0]
	s_waitcnt vmcnt(1)
	v_pk_mul_f32 v[12:13], v[18:19], v[12:13]
	v_pk_mul_f32 v[2:3], v[2:3], v[0:1] op_sel_hi:[1,0]
	s_waitcnt vmcnt(0)
	v_pk_mul_f32 v[10:11], v[26:27], v[10:11]
	v_pk_mul_f32 v[8:9], v[8:9], v[12:13]
	v_pk_mul_f32 v[12:13], v[40:41], v[0:1] op_sel_hi:[1,0]
	v_pk_mul_f32 v[2:3], v[20:21], v[2:3]
	v_pk_mul_f32 v[6:7], v[6:7], v[10:11]
	v_pk_mul_f32 v[10:11], v[38:39], v[0:1] op_sel_hi:[1,0]
	v_pk_mul_f32 v[12:13], v[14:15], v[12:13]
	v_pk_mul_f32 v[14:15], v[62:63], v[2:3]
	v_lshlrev_b32_e32 v2, 16, v5
	v_and_b32_e32 v3, 0xffff0000, v5
	v_pk_mul_f32 v[10:11], v[22:23], v[10:11]
	v_pk_mul_f32 v[22:23], v[32:33], v[0:1] op_sel_hi:[1,0]
	v_pk_mul_f32 v[26:27], v[52:53], v[0:1] op_sel_hi:[1,0]
	v_mul_f32_e32 v4, 0xbfb8aa3b, v2
	v_pk_mul_f32 v[18:19], v[44:45], v[0:1] op_sel_hi:[1,0]
	v_mul_f32_e32 v0, 0xbfb8aa3b, v3
	v_exp_f32_e32 v4, v4
	v_exp_f32_e32 v0, v0
	v_pk_mul_f32 v[22:23], v[28:29], v[22:23]
	v_pk_mul_f32 v[24:25], v[24:25], v[26:27]
	v_add_f32_e32 v4, 1.0, v4
	v_add_f32_e32 v0, 1.0, v0
	v_rcp_f32_e32 v4, v4
	v_rcp_f32_e32 v5, v0
	v_pk_mul_f32 v[22:23], v[68:69], v[22:23]
	v_pk_mul_f32 v[16:17], v[16:17], v[18:19]
	v_pk_mul_f32 v[10:11], v[58:59], v[10:11]
	v_pk_mul_f32 v[2:3], v[4:5], v[2:3]
	v_pk_mul_f32 v[24:25], v[54:55], v[24:25]
	v_pk_mul_f32 v[12:13], v[50:51], v[12:13]
	v_pk_mul_f32 v[16:17], v[2:3], v[16:17]
	v_lshl_add_u64 v[18:19], s[4:5], 0, v[42:43]
	v_cvt_pk_bf16_f32 v2, v6, v7
	v_cvt_pk_bf16_f32 v3, v22, v23
	v_cvt_pk_bf16_f32 v4, v8, v9
	v_cvt_pk_bf16_f32 v5, v14, v15
	global_store_dwordx4 v[18:19], v[2:5], off
	s_nop 1
	v_cvt_pk_bf16_f32 v2, v10, v11
	v_cvt_pk_bf16_f32 v3, v24, v25
	v_cvt_pk_bf16_f32 v4, v12, v13
	v_cvt_pk_bf16_f32 v5, v16, v17
	global_store_dwordx4 v[18:19], v[2:5], off offset:16
